# MoBA gate (q.kbar) rewritten: q chunks loaded together, kbar LDS reads batched+double-buffered, fma chains; plus cmask rewrite
# speedup vs baseline: 1.0027x; 1.0012x over previous
; template<int THRL,int MODE,int DM,bool DRY=false> __device__ __forceinline__ void attn_unit(int b,int h,int qb,const bf16*Q,const bf16*__restrict__ K,const bf16*__restrict__ V,bf16*O,const bf16*__restrict__ Z,const float*__restrict__ XP,const int*__restrict__ TS,volatile unsigned*lw,unsigned nxt,cha ...
;   const int tid=opaque_tid(),lane=tid&63,r32=lane&31,hi=lane>>5; const int wid=__builtin_amdgcn_readfirstlane(tid>>6);
;   const long rowbase=(long)b*SEQ; const int q0=qb*QB;
;   const bf16*Qw=Q+(rowbase+q0+wid*QBLK)*DM+h*D;
;   bf16x8 qr[4];
;   #pragma unroll
;   for(int d0=0;d0<4;++d0)qr[d0]=*reinterpret_cast<const bf16x8*>(&Qw[(long)r32*DM+d0*16+hi*8]);
;   const bf16*Kh=K+rowbase*DM+h*D,*Vh=V+rowbase*DM+h*D;
;   const unsigned lds0=(unsigned)(uintptr_t)shm;
;   float*wsf=(float*)(shm+LDS_WS)+wid*64;
;   const bf16*ksrc_=Kh+(long)lane*DM+wid*8; int tskip=0,fixedref=0; const bf16*ksrc=ksrc_;
;   const bf16*vsrc_=Vh+(long)(16*(wid&3)+(lane>>2))*DM+(wid>>2)*32+(lane&3)*8; const bf16*vsrc=vsrc_;
;   const unsigned kdst=lds0+LDS_K+wid*1024, vdst=lds0+LDS_V+wid*1024;
;     ...
;   const int vb0=(int)(lds0+LDS_V)+((lane>>4)&1)*32+(lane&3)*8+(4*hi+((lane&15)>>2))*64;
;   const char*Kbase=shm+LDS_K; bf16x8 kf[8];
;   const lds_cptr shm3=(lds_cptr)shm; const lds_cptr kp0=shm3+LDS_K+hi*1024+r32*16; const lds_cptr vp0=shm3+LDS_V+((lane>>4)&1)*32+(lane&3)*8+(4*hi+((lane&15)>>2))*64;
;   int NT=(q0+QB)/KVBLK;
;   const int qrel=wid*QBLK+r32;
;   unsigned sel=0u;
;   if constexpr(MODE==1){
;     { const int tsv=__builtin_amdgcn_readfirstlane(TS[qb]); tskip=tsv&0xffff; fixedref=(tsv>>16)&1; }
;     ksrc=ksrc_+(long)tskip*KVBLK*DM; vsrc=vsrc_+(long)tskip*KVBLK*DM; NT-=tskip;
;   }
;   const lds_cptr fsl=(lds_cptr)shm+XOFF+16*hi+tskip*256;
;     ...
;   DMA_K(0,0);DMA_V(0,0);DMA_K(1,SLOTB);
;     ...
;   if constexpr(MODE==0){
;     float*kbs=(float*)(shm+XOFF); unsigned*sm=(unsigned*)(shm+XOFF+2048);
;     kbs[tid]=XP[tid];
;     asm volatile("s_waitcnt vmcnt(0) lgkmcnt(0)\n\ts_barrier":::"memory");
;     if(tid<QB){ unsigned m=(1u<<qb)-1u;
;       if(qb>3){ const bf16*qp=Q+(rowbase+q0+tid)*DM+h*D; float g[8];
;         _Pragma("unroll") for(int n=0;n<8;++n)g[n]=0.f;
;         _Pragma("unroll") for(int c=0;c<8;++c){ const bf16x8 qv=*reinterpret_cast<const bf16x8*>(qp+c*8);
;           _Pragma("unroll") for(int j=0;j<8;++j){ const float qf=__uint_as_float(((unsigned)(unsigned short)qv[j])<<16);
.LBB0_894:
	s_or_b64 exec, exec, s[8:9]
	s_ashr_i32 s8, s10, 31
	s_lshr_b32 s8, s8, 25
	s_add_i32 s8, s10, s8
	s_ashr_i32 s9, s8, 7
	s_and_b32 s8, s8, 0xffffff80
	s_sub_i32 s64, s10, s8
	s_ashr_i32 s65, s64, 31
	s_sub_i32 s92, 0, s9
	s_sub_i32 s95, 7, s9
	s_ashr_i32 s70, s64, 4
	s_lshl_b64 s[8:9], s[64:65], 11
	s_add_u32 s10, s26, s8
	v_mov_b32_e32 v224, v220
	s_addc_u32 s11, s45, s9
	s_ashr_i32 s71, s70, 31
	v_readfirstlane_b32 s93, v224
	s_ashr_i32 s65, s93, 6
	s_lshl_b64 s[8:9], s[70:71], 11
	s_lshl_b32 s94, s95, 8
	s_add_u32 s8, s8, s94
	s_addc_u32 s9, s9, 0
	s_lshl_b32 s96, s65, 5
	s_ashr_i32 s12, s96, 31
	s_add_u32 s14, s8, s96
	s_addc_u32 s12, s9, s12
	s_mulk_i32 s12, 0x1a00
	s_mul_hi_u32 s13, s14, 0x1a00
	s_add_i32 s13, s13, s12
	s_mul_i32 s12, s14, 0x1a00
	s_lshl_b64 s[60:61], s[12:13], 1
	s_add_u32 s12, s28, s60
	s_addc_u32 s13, s29, s61
	s_lshl_b32 s14, s64, 6
	s_and_b32 s14, s14, 0x3c0
	s_lshl_b32 s62, s14, 1
	s_add_u32 s58, s12, s62
	s_addc_u32 s59, s13, 0
	s_mul_i32 s15, s70, 0x1a00000
	s_mul_hi_i32 s14, s70, 0x1a00000
	s_add_u32 s12, s47, s15
	v_and_b32_e32 v237, 31, v224
	s_addc_u32 s13, s84, s14
	v_mul_u32_u24_e32 v16, 0x1a00, v237
	s_add_u32 s12, s12, s62
	v_bfe_u32 v238, v224, 5, 1
	v_lshlrev_b32_e32 v16, 1, v16
	s_addc_u32 s13, s13, 0
	v_lshl_or_b32 v222, v238, 4, v16
	s_add_u32 s15, s85, s15
	v_and_b32_e32 v239, 63, v224
	v_lshl_add_u64 v[16:17], s[58:59], 0, v[222:223]
	s_addc_u32 s16, s86, s14
	flat_load_dwordx4 v[156:159], v[16:17]
	flat_load_dwordx4 v[152:155], v[16:17] offset:32
	flat_load_dwordx4 v[148:151], v[16:17] offset:64
	flat_load_dwordx4 v[144:147], v[16:17] offset:96
	s_add_u32 s14, s15, s62
	v_mul_u32_u24_e32 v16, 0x1a00, v239
	s_addc_u32 s15, s16, 0
	v_lshlrev_b32_e32 v222, 1, v16
	s_lshl_b32 s66, s65, 3
	v_lshl_add_u64 v[16:17], s[12:13], 0, v[222:223]
	s_ashr_i32 s67, s66, 31
	v_lshl_add_u64 v[80:81], s[66:67], 1, v[16:17]
	s_lshl_b32 s12, s65, 4
	v_bfe_u32 v16, v224, 2, 4
	v_and_or_b32 v16, s12, 48, v16
	s_ashr_i32 s12, s93, 3
	s_and_b32 s68, s12, 0xffffffe0
	v_mul_u32_u24_e32 v16, 0x1a00, v16
	s_ashr_i32 s69, s68, 31
	s_lshl_b32 s24, s65, 10
	v_lshlrev_b32_e32 v212, 1, v16
	v_mov_b32_e32 v213, v223
	v_lshlrev_b32_e32 v242, 3, v224
	s_cmp_lg_u32 0, -1
	v_lshl_add_u64 v[16:17], s[14:15], 0, v[212:213]
	v_and_b32_e32 v241, 24, v242
	s_cselect_b32 s12, 0, 0
	v_lshl_add_u64 v[16:17], s[68:69], 1, v[16:17]
	v_lshlrev_b32_e32 v18, 1, v241
	v_mov_b32_e32 v19, v223
	s_add_i32 s91, s24, s12
	s_mov_b32 s12, m0
	s_mov_b32 m0, s91
	s_nop 0
	global_load_lds_dwordx4 v[80:81], off
	s_mov_b32 m0, s12
	v_lshl_add_u64 v[82:83], v[16:17], 0, v[18:19]
	s_add_i32 s71, s91, 0x6000
	s_mov_b32 s12, m0
	s_mov_b32 m0, s71
	s_nop 0
	global_load_lds_dwordx4 v[82:83], off
	s_mov_b32 m0, s12
	v_lshl_add_u64 v[16:17], v[80:81], 0, s[34:35]
	s_add_i32 s12, s91, 0x2000
	s_mov_b32 s13, m0
	s_mov_b32 m0, s12
	s_nop 0
	global_load_lds_dwordx4 v[16:17], off
	s_mov_b32 m0, s13
	v_mov_b64_e32 v[30:31], v[14:15]
	v_mov_b64_e32 v[28:29], v[12:13]
	v_mov_b64_e32 v[26:27], v[10:11]
	v_mov_b64_e32 v[24:25], v[8:9]
	v_mov_b64_e32 v[22:23], v[6:7]
	v_mov_b64_e32 v[20:21], v[4:5]
	v_mov_b64_e32 v[18:19], v[2:3]
	v_mov_b64_e32 v[16:17], v[0:1]
	v_lshl_add_u64 v[32:33], v[80:81], 0, s[36:37]
	v_ashrrev_i32_e32 v225, 31, v224
	s_add_i32 s12, s91, 0x4000
	s_mov_b32 s13, m0
	s_mov_b32 m0, s12
	s_nop 0
	global_load_lds_dwordx4 v[32:33], off
	s_mov_b32 m0, s13
	v_lshl_add_u64 v[32:33], v[224:225], 2, s[10:11]
	flat_load_dword v32, v[32:33]
	v_lshl_add_u32 v33, v224, 2, 0
	v_add_u32_e32 v33, 0x15000, v33
	s_movk_i32 s10, 0x100
	v_cmp_gt_i32_e32 vcc, s10, v224
	s_waitcnt vmcnt(0) lgkmcnt(0)
	ds_write_b32 v33, v32
	s_waitcnt vmcnt(0) lgkmcnt(0)
	s_barrier
	s_and_saveexec_b64 s[72:73], vcc
	s_cbranch_execz .LBB0_898
	s_lshl_b32 s10, -1, s95
	s_not_b32 s10, s10
	s_cmp_lt_u32 s95, 4
	v_mov_b32_e32 v32, s10
	s_cbranch_scc1 .LBB0_897
	v_lshl_add_u64 v[32:33], s[8:9], 0, v[224:225]
	v_mov_b64_e32 v[34:35], s[28:29]
	s_movk_i32 s10, 0x3400
	v_mad_u64_u32 v[34:35], s[8:9], v32, s10, v[34:35]
	v_mad_i32_i24 v35, v33, s10, v35
	s_mov_b32 s63, s25
	v_lshl_add_u64 v[32:33], v[34:35], 0, s[62:63]
	flat_load_dwordx4 v[84:87], v[32:33]
	flat_load_dwordx4 v[88:91], v[32:33] offset:16
	flat_load_dwordx4 v[92:95], v[32:33] offset:32
	flat_load_dwordx4 v[96:99], v[32:33] offset:48
	flat_load_dwordx4 v[100:103], v[32:33] offset:64
	flat_load_dwordx4 v[104:107], v[32:33] offset:80
	flat_load_dwordx4 v[108:111], v[32:33] offset:96
	flat_load_dwordx4 v[112:115], v[32:33] offset:112
	s_mov_b32 s10, 0xff800000
	s_cmp_lg_u32 s95, 4
	s_cselect_b64 s[74:75], -1, 0
	v_mov_b32_e32 v74, 0x15000
	v_mov_b32_e32 v32, 0
	v_mov_b32_e32 v33, 0
	v_mov_b32_e32 v34, 0
	v_mov_b32_e32 v35, 0
	v_mov_b32_e32 v36, 0
	v_mov_b32_e32 v37, 0
	v_mov_b32_e32 v38, 0
	v_mov_b32_e32 v39, 0
	ds_read_b128 v[42:45], v74 offset:0
	ds_read_b128 v[46:49], v74 offset:256
	ds_read_b128 v[50:53], v74 offset:512
	ds_read_b128 v[54:57], v74 offset:768
	ds_read_b128 v[58:61], v74 offset:1024
	ds_read_b128 v[62:65], v74 offset:1280
	ds_read_b128 v[66:69], v74 offset:1536
	ds_read_b128 v[70:73], v74 offset:1792
	s_waitcnt vmcnt(0) lgkmcnt(0)
	ds_read_b128 v[116:119], v74 offset:16
	ds_read_b128 v[120:123], v74 offset:272
	ds_read_b128 v[124:127], v74 offset:528
	ds_read_b128 v[128:131], v74 offset:784
	ds_read_b128 v[132:135], v74 offset:1040
	ds_read_b128 v[136:139], v74 offset:1296
	ds_read_b128 v[140:143], v74 offset:1552
	ds_read_b128 v[76:79], v74 offset:1808
	s_waitcnt lgkmcnt(8)
; template<int THRL,int MODE,int DM,bool DRY=false> __device__ __forceinline__ void attn_unit(int b,int h,int qb,const bf16*Q,const bf16*__restrict__ K,const bf16*__restrict__ V,bf16*O,const bf16*__restrict__ Z,const float*__restrict__ XP,const int*__restrict__ TS,volatile unsigned*lw,unsigned nxt,cha ...
;     ...
;         _Pragma("unroll") for(int c=0;c<8;++c){ const bf16x8 qv=*reinterpret_cast<const bf16x8*>(qp+c*8);
;           _Pragma("unroll") for(int j=0;j<8;++j){ const float qf=__uint_as_float(((unsigned)(unsigned short)qv[j])<<16);
;             _Pragma("unroll") for(int n=0;n<8;++n)g[n]+=qf*kbs[n*64+c*8+j]; } }
	v_lshlrev_b32_e32 v40, 16, v84
	v_fmac_f32_e32 v39, v42, v40
	v_fmac_f32_e32 v38, v46, v40
	v_fmac_f32_e32 v37, v50, v40
	v_fmac_f32_e32 v36, v54, v40
	v_fmac_f32_e32 v35, v58, v40
	v_fmac_f32_e32 v34, v62, v40
	v_fmac_f32_e32 v33, v66, v40
	v_fmac_f32_e32 v32, v70, v40
	v_and_b32_e32 v41, 0xffff0000, v84
	v_fmac_f32_e32 v39, v43, v41
	v_fmac_f32_e32 v38, v47, v41
	v_fmac_f32_e32 v37, v51, v41
	v_fmac_f32_e32 v36, v55, v41
	v_fmac_f32_e32 v35, v59, v41
	v_fmac_f32_e32 v34, v63, v41
	v_fmac_f32_e32 v33, v67, v41
	v_fmac_f32_e32 v32, v71, v41
	v_lshlrev_b32_e32 v40, 16, v85
	v_fmac_f32_e32 v39, v44, v40
	v_fmac_f32_e32 v38, v48, v40
	v_fmac_f32_e32 v37, v52, v40
	v_fmac_f32_e32 v36, v56, v40
	v_fmac_f32_e32 v35, v60, v40
	v_fmac_f32_e32 v34, v64, v40
	v_fmac_f32_e32 v33, v68, v40
	v_fmac_f32_e32 v32, v72, v40
	v_and_b32_e32 v41, 0xffff0000, v85
	v_fmac_f32_e32 v39, v45, v41
	v_fmac_f32_e32 v38, v49, v41
	v_fmac_f32_e32 v37, v53, v41
	v_fmac_f32_e32 v36, v57, v41
	v_fmac_f32_e32 v35, v61, v41
	v_fmac_f32_e32 v34, v65, v41
	v_fmac_f32_e32 v33, v69, v41
	v_fmac_f32_e32 v32, v73, v41
	ds_read_b128 v[42:45], v74 offset:32
	ds_read_b128 v[46:49], v74 offset:288
	ds_read_b128 v[50:53], v74 offset:544
	ds_read_b128 v[54:57], v74 offset:800
	ds_read_b128 v[58:61], v74 offset:1056
	ds_read_b128 v[62:65], v74 offset:1312
	ds_read_b128 v[66:69], v74 offset:1568
	ds_read_b128 v[70:73], v74 offset:1824
	s_waitcnt lgkmcnt(8)
	v_lshlrev_b32_e32 v40, 16, v86
	v_fmac_f32_e32 v39, v116, v40
	v_fmac_f32_e32 v38, v120, v40
	v_fmac_f32_e32 v37, v124, v40
	v_fmac_f32_e32 v36, v128, v40
	v_fmac_f32_e32 v35, v132, v40
	v_fmac_f32_e32 v34, v136, v40
	v_fmac_f32_e32 v33, v140, v40
	v_fmac_f32_e32 v32, v76, v40
	v_and_b32_e32 v41, 0xffff0000, v86
	v_fmac_f32_e32 v39, v117, v41
	v_fmac_f32_e32 v38, v121, v41
	v_fmac_f32_e32 v37, v125, v41
	v_fmac_f32_e32 v36, v129, v41
	v_fmac_f32_e32 v35, v133, v41
	v_fmac_f32_e32 v34, v137, v41
	v_fmac_f32_e32 v33, v141, v41
	v_fmac_f32_e32 v32, v77, v41
	v_lshlrev_b32_e32 v40, 16, v87
	v_fmac_f32_e32 v39, v118, v40
	v_fmac_f32_e32 v38, v122, v40
	v_fmac_f32_e32 v37, v126, v40
	v_fmac_f32_e32 v36, v130, v40
	v_fmac_f32_e32 v35, v134, v40
	v_fmac_f32_e32 v34, v138, v40
	v_fmac_f32_e32 v33, v142, v40
	v_fmac_f32_e32 v32, v78, v40
	v_and_b32_e32 v41, 0xffff0000, v87
	v_fmac_f32_e32 v39, v119, v41
	v_fmac_f32_e32 v38, v123, v41
	v_fmac_f32_e32 v37, v127, v41
	v_fmac_f32_e32 v36, v131, v41
	v_fmac_f32_e32 v35, v135, v41
	v_fmac_f32_e32 v34, v139, v41
	v_fmac_f32_e32 v33, v143, v41
	v_fmac_f32_e32 v32, v79, v41
	ds_read_b128 v[116:119], v74 offset:48
	ds_read_b128 v[120:123], v74 offset:304
	ds_read_b128 v[124:127], v74 offset:560
	ds_read_b128 v[128:131], v74 offset:816
	ds_read_b128 v[132:135], v74 offset:1072
	ds_read_b128 v[136:139], v74 offset:1328
	ds_read_b128 v[140:143], v74 offset:1584
	ds_read_b128 v[76:79], v74 offset:1840
	s_waitcnt lgkmcnt(8)
	v_lshlrev_b32_e32 v40, 16, v88
	v_fmac_f32_e32 v39, v42, v40
	v_fmac_f32_e32 v38, v46, v40
	v_fmac_f32_e32 v37, v50, v40
	v_fmac_f32_e32 v36, v54, v40
	v_fmac_f32_e32 v35, v58, v40
	v_fmac_f32_e32 v34, v62, v40
	v_fmac_f32_e32 v33, v66, v40
	v_fmac_f32_e32 v32, v70, v40
	v_and_b32_e32 v41, 0xffff0000, v88
	v_fmac_f32_e32 v39, v43, v41
	v_fmac_f32_e32 v38, v47, v41
	v_fmac_f32_e32 v37, v51, v41
	v_fmac_f32_e32 v36, v55, v41
	v_fmac_f32_e32 v35, v59, v41
	v_fmac_f32_e32 v34, v63, v41
	v_fmac_f32_e32 v33, v67, v41
	v_fmac_f32_e32 v32, v71, v41
	v_lshlrev_b32_e32 v40, 16, v89
	v_fmac_f32_e32 v39, v44, v40
	v_fmac_f32_e32 v38, v48, v40
	v_fmac_f32_e32 v37, v52, v40
	v_fmac_f32_e32 v36, v56, v40
	v_fmac_f32_e32 v35, v60, v40
	v_fmac_f32_e32 v34, v64, v40
	v_fmac_f32_e32 v33, v68, v40
	v_fmac_f32_e32 v32, v72, v40
	v_and_b32_e32 v41, 0xffff0000, v89
	v_fmac_f32_e32 v39, v45, v41
	v_fmac_f32_e32 v38, v49, v41
	v_fmac_f32_e32 v37, v53, v41
	v_fmac_f32_e32 v36, v57, v41
	v_fmac_f32_e32 v35, v61, v41
	v_fmac_f32_e32 v34, v65, v41
	v_fmac_f32_e32 v33, v69, v41
	v_fmac_f32_e32 v32, v73, v41
	ds_read_b128 v[42:45], v74 offset:64
	ds_read_b128 v[46:49], v74 offset:320
	ds_read_b128 v[50:53], v74 offset:576
	ds_read_b128 v[54:57], v74 offset:832
	ds_read_b128 v[58:61], v74 offset:1088
	ds_read_b128 v[62:65], v74 offset:1344
	ds_read_b128 v[66:69], v74 offset:1600
	ds_read_b128 v[70:73], v74 offset:1856
	s_waitcnt lgkmcnt(8)
	v_lshlrev_b32_e32 v40, 16, v90
	v_fmac_f32_e32 v39, v116, v40
	v_fmac_f32_e32 v38, v120, v40
	v_fmac_f32_e32 v37, v124, v40
	v_fmac_f32_e32 v36, v128, v40
	v_fmac_f32_e32 v35, v132, v40
	v_fmac_f32_e32 v34, v136, v40
	v_fmac_f32_e32 v33, v140, v40
	v_fmac_f32_e32 v32, v76, v40
	v_and_b32_e32 v41, 0xffff0000, v90
	v_fmac_f32_e32 v39, v117, v41
	v_fmac_f32_e32 v38, v121, v41
	v_fmac_f32_e32 v37, v125, v41
	v_fmac_f32_e32 v36, v129, v41
	v_fmac_f32_e32 v35, v133, v41
	v_fmac_f32_e32 v34, v137, v41
	v_fmac_f32_e32 v33, v141, v41
	v_fmac_f32_e32 v32, v77, v41
	v_lshlrev_b32_e32 v40, 16, v91
	v_fmac_f32_e32 v39, v118, v40
	v_fmac_f32_e32 v38, v122, v40
	v_fmac_f32_e32 v37, v126, v40
	v_fmac_f32_e32 v36, v130, v40
	v_fmac_f32_e32 v35, v134, v40
	v_fmac_f32_e32 v34, v138, v40
	v_fmac_f32_e32 v33, v142, v40
	v_fmac_f32_e32 v32, v78, v40
	v_and_b32_e32 v41, 0xffff0000, v91
	v_fmac_f32_e32 v39, v119, v41
	v_fmac_f32_e32 v38, v123, v41
	v_fmac_f32_e32 v37, v127, v41
	v_fmac_f32_e32 v36, v131, v41
	v_fmac_f32_e32 v35, v135, v41
	v_fmac_f32_e32 v34, v139, v41
	v_fmac_f32_e32 v33, v143, v41
	v_fmac_f32_e32 v32, v79, v41
	ds_read_b128 v[116:119], v74 offset:80
	ds_read_b128 v[120:123], v74 offset:336
	ds_read_b128 v[124:127], v74 offset:592
	ds_read_b128 v[128:131], v74 offset:848
	ds_read_b128 v[132:135], v74 offset:1104
	ds_read_b128 v[136:139], v74 offset:1360
	ds_read_b128 v[140:143], v74 offset:1616
	ds_read_b128 v[76:79], v74 offset:1872
	s_waitcnt lgkmcnt(8)
; template<int THRL,int MODE,int DM,bool DRY=false> __device__ __forceinline__ void attn_unit(int b,int h,int qb,const bf16*Q,const bf16*__restrict__ K,const bf16*__restrict__ V,bf16*O,const bf16*__restrict__ Z,const float*__restrict__ XP,const int*__restrict__ TS,volatile unsigned*lw,unsigned nxt,cha ...
;     ...
;         _Pragma("unroll") for(int c=0;c<8;++c){ const bf16x8 qv=*reinterpret_cast<const bf16x8*>(qp+c*8);
;           _Pragma("unroll") for(int j=0;j<8;++j){ const float qf=__uint_as_float(((unsigned)(unsigned short)qv[j])<<16);
;             _Pragma("unroll") for(int n=0;n<8;++n)g[n]+=qf*kbs[n*64+c*8+j]; } }
	v_lshlrev_b32_e32 v40, 16, v92
	v_fmac_f32_e32 v39, v42, v40
	v_fmac_f32_e32 v38, v46, v40
	v_fmac_f32_e32 v37, v50, v40
	v_fmac_f32_e32 v36, v54, v40
	v_fmac_f32_e32 v35, v58, v40
	v_fmac_f32_e32 v34, v62, v40
	v_fmac_f32_e32 v33, v66, v40
	v_fmac_f32_e32 v32, v70, v40
	v_and_b32_e32 v41, 0xffff0000, v92
	v_fmac_f32_e32 v39, v43, v41
	v_fmac_f32_e32 v38, v47, v41
	v_fmac_f32_e32 v37, v51, v41
	v_fmac_f32_e32 v36, v55, v41
	v_fmac_f32_e32 v35, v59, v41
	v_fmac_f32_e32 v34, v63, v41
	v_fmac_f32_e32 v33, v67, v41
	v_fmac_f32_e32 v32, v71, v41
	v_lshlrev_b32_e32 v40, 16, v93
	v_fmac_f32_e32 v39, v44, v40
	v_fmac_f32_e32 v38, v48, v40
	v_fmac_f32_e32 v37, v52, v40
	v_fmac_f32_e32 v36, v56, v40
	v_fmac_f32_e32 v35, v60, v40
	v_fmac_f32_e32 v34, v64, v40
	v_fmac_f32_e32 v33, v68, v40
	v_fmac_f32_e32 v32, v72, v40
	v_and_b32_e32 v41, 0xffff0000, v93
	v_fmac_f32_e32 v39, v45, v41
	v_fmac_f32_e32 v38, v49, v41
	v_fmac_f32_e32 v37, v53, v41
	v_fmac_f32_e32 v36, v57, v41
	v_fmac_f32_e32 v35, v61, v41
	v_fmac_f32_e32 v34, v65, v41
	v_fmac_f32_e32 v33, v69, v41
	v_fmac_f32_e32 v32, v73, v41
	ds_read_b128 v[42:45], v74 offset:96
	ds_read_b128 v[46:49], v74 offset:352
	ds_read_b128 v[50:53], v74 offset:608
	ds_read_b128 v[54:57], v74 offset:864
	ds_read_b128 v[58:61], v74 offset:1120
	ds_read_b128 v[62:65], v74 offset:1376
	ds_read_b128 v[66:69], v74 offset:1632
	ds_read_b128 v[70:73], v74 offset:1888
	s_waitcnt lgkmcnt(8)
	v_lshlrev_b32_e32 v40, 16, v94
	v_fmac_f32_e32 v39, v116, v40
	v_fmac_f32_e32 v38, v120, v40
	v_fmac_f32_e32 v37, v124, v40
	v_fmac_f32_e32 v36, v128, v40
	v_fmac_f32_e32 v35, v132, v40
	v_fmac_f32_e32 v34, v136, v40
	v_fmac_f32_e32 v33, v140, v40
	v_fmac_f32_e32 v32, v76, v40
	v_and_b32_e32 v41, 0xffff0000, v94
	v_fmac_f32_e32 v39, v117, v41
	v_fmac_f32_e32 v38, v121, v41
	v_fmac_f32_e32 v37, v125, v41
	v_fmac_f32_e32 v36, v129, v41
	v_fmac_f32_e32 v35, v133, v41
	v_fmac_f32_e32 v34, v137, v41
	v_fmac_f32_e32 v33, v141, v41
	v_fmac_f32_e32 v32, v77, v41
	v_lshlrev_b32_e32 v40, 16, v95
	v_fmac_f32_e32 v39, v118, v40
	v_fmac_f32_e32 v38, v122, v40
	v_fmac_f32_e32 v37, v126, v40
	v_fmac_f32_e32 v36, v130, v40
	v_fmac_f32_e32 v35, v134, v40
	v_fmac_f32_e32 v34, v138, v40
	v_fmac_f32_e32 v33, v142, v40
	v_fmac_f32_e32 v32, v78, v40
	v_and_b32_e32 v41, 0xffff0000, v95
	v_fmac_f32_e32 v39, v119, v41
	v_fmac_f32_e32 v38, v123, v41
	v_fmac_f32_e32 v37, v127, v41
	v_fmac_f32_e32 v36, v131, v41
	v_fmac_f32_e32 v35, v135, v41
	v_fmac_f32_e32 v34, v139, v41
	v_fmac_f32_e32 v33, v143, v41
	v_fmac_f32_e32 v32, v79, v41
	ds_read_b128 v[116:119], v74 offset:112
	ds_read_b128 v[120:123], v74 offset:368
	ds_read_b128 v[124:127], v74 offset:624
	ds_read_b128 v[128:131], v74 offset:880
	ds_read_b128 v[132:135], v74 offset:1136
	ds_read_b128 v[136:139], v74 offset:1392
	ds_read_b128 v[140:143], v74 offset:1648
	ds_read_b128 v[76:79], v74 offset:1904
	s_waitcnt lgkmcnt(8)
	v_lshlrev_b32_e32 v40, 16, v96
	v_fmac_f32_e32 v39, v42, v40
	v_fmac_f32_e32 v38, v46, v40
	v_fmac_f32_e32 v37, v50, v40
	v_fmac_f32_e32 v36, v54, v40
	v_fmac_f32_e32 v35, v58, v40
	v_fmac_f32_e32 v34, v62, v40
	v_fmac_f32_e32 v33, v66, v40
	v_fmac_f32_e32 v32, v70, v40
	v_and_b32_e32 v41, 0xffff0000, v96
	v_fmac_f32_e32 v39, v43, v41
	v_fmac_f32_e32 v38, v47, v41
	v_fmac_f32_e32 v37, v51, v41
	v_fmac_f32_e32 v36, v55, v41
	v_fmac_f32_e32 v35, v59, v41
	v_fmac_f32_e32 v34, v63, v41
	v_fmac_f32_e32 v33, v67, v41
	v_fmac_f32_e32 v32, v71, v41
	v_lshlrev_b32_e32 v40, 16, v97
	v_fmac_f32_e32 v39, v44, v40
	v_fmac_f32_e32 v38, v48, v40
	v_fmac_f32_e32 v37, v52, v40
	v_fmac_f32_e32 v36, v56, v40
	v_fmac_f32_e32 v35, v60, v40
	v_fmac_f32_e32 v34, v64, v40
	v_fmac_f32_e32 v33, v68, v40
	v_fmac_f32_e32 v32, v72, v40
	v_and_b32_e32 v41, 0xffff0000, v97
	v_fmac_f32_e32 v39, v45, v41
	v_fmac_f32_e32 v38, v49, v41
	v_fmac_f32_e32 v37, v53, v41
	v_fmac_f32_e32 v36, v57, v41
	v_fmac_f32_e32 v35, v61, v41
	v_fmac_f32_e32 v34, v65, v41
	v_fmac_f32_e32 v33, v69, v41
	v_fmac_f32_e32 v32, v73, v41
	ds_read_b128 v[42:45], v74 offset:128
	ds_read_b128 v[46:49], v74 offset:384
	ds_read_b128 v[50:53], v74 offset:640
	ds_read_b128 v[54:57], v74 offset:896
	ds_read_b128 v[58:61], v74 offset:1152
	ds_read_b128 v[62:65], v74 offset:1408
	ds_read_b128 v[66:69], v74 offset:1664
	ds_read_b128 v[70:73], v74 offset:1920
	s_waitcnt lgkmcnt(8)
	v_lshlrev_b32_e32 v40, 16, v98
	v_fmac_f32_e32 v39, v116, v40
	v_fmac_f32_e32 v38, v120, v40
	v_fmac_f32_e32 v37, v124, v40
	v_fmac_f32_e32 v36, v128, v40
	v_fmac_f32_e32 v35, v132, v40
	v_fmac_f32_e32 v34, v136, v40
	v_fmac_f32_e32 v33, v140, v40
	v_fmac_f32_e32 v32, v76, v40
	v_and_b32_e32 v41, 0xffff0000, v98
	v_fmac_f32_e32 v39, v117, v41
	v_fmac_f32_e32 v38, v121, v41
	v_fmac_f32_e32 v37, v125, v41
	v_fmac_f32_e32 v36, v129, v41
	v_fmac_f32_e32 v35, v133, v41
	v_fmac_f32_e32 v34, v137, v41
	v_fmac_f32_e32 v33, v141, v41
	v_fmac_f32_e32 v32, v77, v41
	v_lshlrev_b32_e32 v40, 16, v99
	v_fmac_f32_e32 v39, v118, v40
	v_fmac_f32_e32 v38, v122, v40
	v_fmac_f32_e32 v37, v126, v40
	v_fmac_f32_e32 v36, v130, v40
	v_fmac_f32_e32 v35, v134, v40
	v_fmac_f32_e32 v34, v138, v40
	v_fmac_f32_e32 v33, v142, v40
	v_fmac_f32_e32 v32, v78, v40
	v_and_b32_e32 v41, 0xffff0000, v99
	v_fmac_f32_e32 v39, v119, v41
	v_fmac_f32_e32 v38, v123, v41
	v_fmac_f32_e32 v37, v127, v41
	v_fmac_f32_e32 v36, v131, v41
	v_fmac_f32_e32 v35, v135, v41
	v_fmac_f32_e32 v34, v139, v41
	v_fmac_f32_e32 v33, v143, v41
	v_fmac_f32_e32 v32, v79, v41
	ds_read_b128 v[116:119], v74 offset:144
	ds_read_b128 v[120:123], v74 offset:400
	ds_read_b128 v[124:127], v74 offset:656
	ds_read_b128 v[128:131], v74 offset:912
	ds_read_b128 v[132:135], v74 offset:1168
	ds_read_b128 v[136:139], v74 offset:1424
	ds_read_b128 v[140:143], v74 offset:1680
	ds_read_b128 v[76:79], v74 offset:1936
	s_waitcnt lgkmcnt(8)
; template<int THRL,int MODE,int DM,bool DRY=false> __device__ __forceinline__ void attn_unit(int b,int h,int qb,const bf16*Q,const bf16*__restrict__ K,const bf16*__restrict__ V,bf16*O,const bf16*__restrict__ Z,const float*__restrict__ XP,const int*__restrict__ TS,volatile unsigned*lw,unsigned nxt,cha ...
;     ...
;         _Pragma("unroll") for(int c=0;c<8;++c){ const bf16x8 qv=*reinterpret_cast<const bf16x8*>(qp+c*8);
;           _Pragma("unroll") for(int j=0;j<8;++j){ const float qf=__uint_as_float(((unsigned)(unsigned short)qv[j])<<16);
;             _Pragma("unroll") for(int n=0;n<8;++n)g[n]+=qf*kbs[n*64+c*8+j]; } }
	v_lshlrev_b32_e32 v40, 16, v100
	v_fmac_f32_e32 v39, v42, v40
	v_fmac_f32_e32 v38, v46, v40
	v_fmac_f32_e32 v37, v50, v40
	v_fmac_f32_e32 v36, v54, v40
	v_fmac_f32_e32 v35, v58, v40
	v_fmac_f32_e32 v34, v62, v40
	v_fmac_f32_e32 v33, v66, v40
	v_fmac_f32_e32 v32, v70, v40
	v_and_b32_e32 v41, 0xffff0000, v100
	v_fmac_f32_e32 v39, v43, v41
	v_fmac_f32_e32 v38, v47, v41
	v_fmac_f32_e32 v37, v51, v41
	v_fmac_f32_e32 v36, v55, v41
	v_fmac_f32_e32 v35, v59, v41
	v_fmac_f32_e32 v34, v63, v41
	v_fmac_f32_e32 v33, v67, v41
	v_fmac_f32_e32 v32, v71, v41
	v_lshlrev_b32_e32 v40, 16, v101
	v_fmac_f32_e32 v39, v44, v40
	v_fmac_f32_e32 v38, v48, v40
	v_fmac_f32_e32 v37, v52, v40
	v_fmac_f32_e32 v36, v56, v40
	v_fmac_f32_e32 v35, v60, v40
	v_fmac_f32_e32 v34, v64, v40
	v_fmac_f32_e32 v33, v68, v40
	v_fmac_f32_e32 v32, v72, v40
	v_and_b32_e32 v41, 0xffff0000, v101
	v_fmac_f32_e32 v39, v45, v41
	v_fmac_f32_e32 v38, v49, v41
	v_fmac_f32_e32 v37, v53, v41
	v_fmac_f32_e32 v36, v57, v41
	v_fmac_f32_e32 v35, v61, v41
	v_fmac_f32_e32 v34, v65, v41
	v_fmac_f32_e32 v33, v69, v41
	v_fmac_f32_e32 v32, v73, v41
	ds_read_b128 v[42:45], v74 offset:160
	ds_read_b128 v[46:49], v74 offset:416
	ds_read_b128 v[50:53], v74 offset:672
	ds_read_b128 v[54:57], v74 offset:928
	ds_read_b128 v[58:61], v74 offset:1184
	ds_read_b128 v[62:65], v74 offset:1440
	ds_read_b128 v[66:69], v74 offset:1696
	ds_read_b128 v[70:73], v74 offset:1952
	s_waitcnt lgkmcnt(8)
	v_lshlrev_b32_e32 v40, 16, v102
	v_fmac_f32_e32 v39, v116, v40
	v_fmac_f32_e32 v38, v120, v40
	v_fmac_f32_e32 v37, v124, v40
	v_fmac_f32_e32 v36, v128, v40
	v_fmac_f32_e32 v35, v132, v40
	v_fmac_f32_e32 v34, v136, v40
	v_fmac_f32_e32 v33, v140, v40
	v_fmac_f32_e32 v32, v76, v40
	v_and_b32_e32 v41, 0xffff0000, v102
	v_fmac_f32_e32 v39, v117, v41
	v_fmac_f32_e32 v38, v121, v41
	v_fmac_f32_e32 v37, v125, v41
	v_fmac_f32_e32 v36, v129, v41
	v_fmac_f32_e32 v35, v133, v41
	v_fmac_f32_e32 v34, v137, v41
	v_fmac_f32_e32 v33, v141, v41
	v_fmac_f32_e32 v32, v77, v41
	v_lshlrev_b32_e32 v40, 16, v103
	v_fmac_f32_e32 v39, v118, v40
	v_fmac_f32_e32 v38, v122, v40
	v_fmac_f32_e32 v37, v126, v40
	v_fmac_f32_e32 v36, v130, v40
	v_fmac_f32_e32 v35, v134, v40
	v_fmac_f32_e32 v34, v138, v40
	v_fmac_f32_e32 v33, v142, v40
	v_fmac_f32_e32 v32, v78, v40
	v_and_b32_e32 v41, 0xffff0000, v103
	v_fmac_f32_e32 v39, v119, v41
	v_fmac_f32_e32 v38, v123, v41
	v_fmac_f32_e32 v37, v127, v41
	v_fmac_f32_e32 v36, v131, v41
	v_fmac_f32_e32 v35, v135, v41
	v_fmac_f32_e32 v34, v139, v41
	v_fmac_f32_e32 v33, v143, v41
	v_fmac_f32_e32 v32, v79, v41
	ds_read_b128 v[116:119], v74 offset:176
	ds_read_b128 v[120:123], v74 offset:432
	ds_read_b128 v[124:127], v74 offset:688
	ds_read_b128 v[128:131], v74 offset:944
	ds_read_b128 v[132:135], v74 offset:1200
	ds_read_b128 v[136:139], v74 offset:1456
	ds_read_b128 v[140:143], v74 offset:1712
	ds_read_b128 v[76:79], v74 offset:1968
	s_waitcnt lgkmcnt(8)
	v_lshlrev_b32_e32 v40, 16, v104
	v_fmac_f32_e32 v39, v42, v40
	v_fmac_f32_e32 v38, v46, v40
	v_fmac_f32_e32 v37, v50, v40
	v_fmac_f32_e32 v36, v54, v40
	v_fmac_f32_e32 v35, v58, v40
	v_fmac_f32_e32 v34, v62, v40
	v_fmac_f32_e32 v33, v66, v40
	v_fmac_f32_e32 v32, v70, v40
	v_and_b32_e32 v41, 0xffff0000, v104
	v_fmac_f32_e32 v39, v43, v41
	v_fmac_f32_e32 v38, v47, v41
	v_fmac_f32_e32 v37, v51, v41
	v_fmac_f32_e32 v36, v55, v41
	v_fmac_f32_e32 v35, v59, v41
	v_fmac_f32_e32 v34, v63, v41
	v_fmac_f32_e32 v33, v67, v41
	v_fmac_f32_e32 v32, v71, v41
	v_lshlrev_b32_e32 v40, 16, v105
	v_fmac_f32_e32 v39, v44, v40
	v_fmac_f32_e32 v38, v48, v40
	v_fmac_f32_e32 v37, v52, v40
	v_fmac_f32_e32 v36, v56, v40
	v_fmac_f32_e32 v35, v60, v40
	v_fmac_f32_e32 v34, v64, v40
	v_fmac_f32_e32 v33, v68, v40
	v_fmac_f32_e32 v32, v72, v40
	v_and_b32_e32 v41, 0xffff0000, v105
	v_fmac_f32_e32 v39, v45, v41
	v_fmac_f32_e32 v38, v49, v41
	v_fmac_f32_e32 v37, v53, v41
	v_fmac_f32_e32 v36, v57, v41
	v_fmac_f32_e32 v35, v61, v41
	v_fmac_f32_e32 v34, v65, v41
	v_fmac_f32_e32 v33, v69, v41
	v_fmac_f32_e32 v32, v73, v41
	ds_read_b128 v[42:45], v74 offset:192
	ds_read_b128 v[46:49], v74 offset:448
	ds_read_b128 v[50:53], v74 offset:704
	ds_read_b128 v[54:57], v74 offset:960
	ds_read_b128 v[58:61], v74 offset:1216
	ds_read_b128 v[62:65], v74 offset:1472
	ds_read_b128 v[66:69], v74 offset:1728
	ds_read_b128 v[70:73], v74 offset:1984
	s_waitcnt lgkmcnt(8)
	v_lshlrev_b32_e32 v40, 16, v106
	v_fmac_f32_e32 v39, v116, v40
	v_fmac_f32_e32 v38, v120, v40
	v_fmac_f32_e32 v37, v124, v40
	v_fmac_f32_e32 v36, v128, v40
	v_fmac_f32_e32 v35, v132, v40
	v_fmac_f32_e32 v34, v136, v40
	v_fmac_f32_e32 v33, v140, v40
	v_fmac_f32_e32 v32, v76, v40
	v_and_b32_e32 v41, 0xffff0000, v106
	v_fmac_f32_e32 v39, v117, v41
	v_fmac_f32_e32 v38, v121, v41
	v_fmac_f32_e32 v37, v125, v41
	v_fmac_f32_e32 v36, v129, v41
	v_fmac_f32_e32 v35, v133, v41
	v_fmac_f32_e32 v34, v137, v41
	v_fmac_f32_e32 v33, v141, v41
	v_fmac_f32_e32 v32, v77, v41
	v_lshlrev_b32_e32 v40, 16, v107
	v_fmac_f32_e32 v39, v118, v40
	v_fmac_f32_e32 v38, v122, v40
	v_fmac_f32_e32 v37, v126, v40
	v_fmac_f32_e32 v36, v130, v40
	v_fmac_f32_e32 v35, v134, v40
	v_fmac_f32_e32 v34, v138, v40
	v_fmac_f32_e32 v33, v142, v40
	v_fmac_f32_e32 v32, v78, v40
	v_and_b32_e32 v41, 0xffff0000, v107
	v_fmac_f32_e32 v39, v119, v41
	v_fmac_f32_e32 v38, v123, v41
	v_fmac_f32_e32 v37, v127, v41
	v_fmac_f32_e32 v36, v131, v41
	v_fmac_f32_e32 v35, v135, v41
	v_fmac_f32_e32 v34, v139, v41
	v_fmac_f32_e32 v33, v143, v41
	v_fmac_f32_e32 v32, v79, v41
	ds_read_b128 v[116:119], v74 offset:208
	ds_read_b128 v[120:123], v74 offset:464
	ds_read_b128 v[124:127], v74 offset:720
	ds_read_b128 v[128:131], v74 offset:976
	ds_read_b128 v[132:135], v74 offset:1232
	ds_read_b128 v[136:139], v74 offset:1488
	ds_read_b128 v[140:143], v74 offset:1744
	ds_read_b128 v[76:79], v74 offset:2000
	s_waitcnt lgkmcnt(8)
; template<int THRL,int MODE,int DM,bool DRY=false> __device__ __forceinline__ void attn_unit(int b,int h,int qb,const bf16*Q,const bf16*__restrict__ K,const bf16*__restrict__ V,bf16*O,const bf16*__restrict__ Z,const float*__restrict__ XP,const int*__restrict__ TS,volatile unsigned*lw,unsigned nxt,cha ...
;     ...
;         _Pragma("unroll") for(int c=0;c<8;++c){ const bf16x8 qv=*reinterpret_cast<const bf16x8*>(qp+c*8);
;           _Pragma("unroll") for(int j=0;j<8;++j){ const float qf=__uint_as_float(((unsigned)(unsigned short)qv[j])<<16);
;             _Pragma("unroll") for(int n=0;n<8;++n)g[n]+=qf*kbs[n*64+c*8+j]; } }
	v_lshlrev_b32_e32 v40, 16, v108
	v_fmac_f32_e32 v39, v42, v40
	v_fmac_f32_e32 v38, v46, v40
	v_fmac_f32_e32 v37, v50, v40
	v_fmac_f32_e32 v36, v54, v40
	v_fmac_f32_e32 v35, v58, v40
	v_fmac_f32_e32 v34, v62, v40
	v_fmac_f32_e32 v33, v66, v40
	v_fmac_f32_e32 v32, v70, v40
	v_and_b32_e32 v41, 0xffff0000, v108
	v_fmac_f32_e32 v39, v43, v41
	v_fmac_f32_e32 v38, v47, v41
	v_fmac_f32_e32 v37, v51, v41
	v_fmac_f32_e32 v36, v55, v41
	v_fmac_f32_e32 v35, v59, v41
	v_fmac_f32_e32 v34, v63, v41
	v_fmac_f32_e32 v33, v67, v41
	v_fmac_f32_e32 v32, v71, v41
	v_lshlrev_b32_e32 v40, 16, v109
	v_fmac_f32_e32 v39, v44, v40
	v_fmac_f32_e32 v38, v48, v40
	v_fmac_f32_e32 v37, v52, v40
	v_fmac_f32_e32 v36, v56, v40
	v_fmac_f32_e32 v35, v60, v40
	v_fmac_f32_e32 v34, v64, v40
	v_fmac_f32_e32 v33, v68, v40
	v_fmac_f32_e32 v32, v72, v40
	v_and_b32_e32 v41, 0xffff0000, v109
	v_fmac_f32_e32 v39, v45, v41
	v_fmac_f32_e32 v38, v49, v41
	v_fmac_f32_e32 v37, v53, v41
	v_fmac_f32_e32 v36, v57, v41
	v_fmac_f32_e32 v35, v61, v41
	v_fmac_f32_e32 v34, v65, v41
	v_fmac_f32_e32 v33, v69, v41
	v_fmac_f32_e32 v32, v73, v41
	ds_read_b128 v[42:45], v74 offset:224
	ds_read_b128 v[46:49], v74 offset:480
	ds_read_b128 v[50:53], v74 offset:736
	ds_read_b128 v[54:57], v74 offset:992
	ds_read_b128 v[58:61], v74 offset:1248
	ds_read_b128 v[62:65], v74 offset:1504
	ds_read_b128 v[66:69], v74 offset:1760
	ds_read_b128 v[70:73], v74 offset:2016
	s_waitcnt lgkmcnt(8)
	v_lshlrev_b32_e32 v40, 16, v110
	v_fmac_f32_e32 v39, v116, v40
	v_fmac_f32_e32 v38, v120, v40
	v_fmac_f32_e32 v37, v124, v40
	v_fmac_f32_e32 v36, v128, v40
	v_fmac_f32_e32 v35, v132, v40
	v_fmac_f32_e32 v34, v136, v40
	v_fmac_f32_e32 v33, v140, v40
	v_fmac_f32_e32 v32, v76, v40
	v_and_b32_e32 v41, 0xffff0000, v110
	v_fmac_f32_e32 v39, v117, v41
	v_fmac_f32_e32 v38, v121, v41
	v_fmac_f32_e32 v37, v125, v41
	v_fmac_f32_e32 v36, v129, v41
	v_fmac_f32_e32 v35, v133, v41
	v_fmac_f32_e32 v34, v137, v41
	v_fmac_f32_e32 v33, v141, v41
	v_fmac_f32_e32 v32, v77, v41
	v_lshlrev_b32_e32 v40, 16, v111
	v_fmac_f32_e32 v39, v118, v40
	v_fmac_f32_e32 v38, v122, v40
	v_fmac_f32_e32 v37, v126, v40
	v_fmac_f32_e32 v36, v130, v40
	v_fmac_f32_e32 v35, v134, v40
	v_fmac_f32_e32 v34, v138, v40
	v_fmac_f32_e32 v33, v142, v40
	v_fmac_f32_e32 v32, v78, v40
	v_and_b32_e32 v41, 0xffff0000, v111
	v_fmac_f32_e32 v39, v119, v41
	v_fmac_f32_e32 v38, v123, v41
	v_fmac_f32_e32 v37, v127, v41
	v_fmac_f32_e32 v36, v131, v41
	v_fmac_f32_e32 v35, v135, v41
	v_fmac_f32_e32 v34, v139, v41
	v_fmac_f32_e32 v33, v143, v41
	v_fmac_f32_e32 v32, v79, v41
	ds_read_b128 v[116:119], v74 offset:240
	ds_read_b128 v[120:123], v74 offset:496
	ds_read_b128 v[124:127], v74 offset:752
	ds_read_b128 v[128:131], v74 offset:1008
	ds_read_b128 v[132:135], v74 offset:1264
	ds_read_b128 v[136:139], v74 offset:1520
	ds_read_b128 v[140:143], v74 offset:1776
	ds_read_b128 v[76:79], v74 offset:2032
	s_waitcnt lgkmcnt(8)
	v_lshlrev_b32_e32 v40, 16, v112
	v_fmac_f32_e32 v39, v42, v40
	v_fmac_f32_e32 v38, v46, v40
	v_fmac_f32_e32 v37, v50, v40
	v_fmac_f32_e32 v36, v54, v40
	v_fmac_f32_e32 v35, v58, v40
	v_fmac_f32_e32 v34, v62, v40
	v_fmac_f32_e32 v33, v66, v40
	v_fmac_f32_e32 v32, v70, v40
	v_and_b32_e32 v41, 0xffff0000, v112
	v_fmac_f32_e32 v39, v43, v41
	v_fmac_f32_e32 v38, v47, v41
	v_fmac_f32_e32 v37, v51, v41
	v_fmac_f32_e32 v36, v55, v41
	v_fmac_f32_e32 v35, v59, v41
	v_fmac_f32_e32 v34, v63, v41
	v_fmac_f32_e32 v33, v67, v41
	v_fmac_f32_e32 v32, v71, v41
	v_lshlrev_b32_e32 v40, 16, v113
	v_fmac_f32_e32 v39, v44, v40
	v_fmac_f32_e32 v38, v48, v40
	v_fmac_f32_e32 v37, v52, v40
	v_fmac_f32_e32 v36, v56, v40
	v_fmac_f32_e32 v35, v60, v40
	v_fmac_f32_e32 v34, v64, v40
	v_fmac_f32_e32 v33, v68, v40
	v_fmac_f32_e32 v32, v72, v40
	v_and_b32_e32 v41, 0xffff0000, v113
	v_fmac_f32_e32 v39, v45, v41
	v_fmac_f32_e32 v38, v49, v41
	v_fmac_f32_e32 v37, v53, v41
	v_fmac_f32_e32 v36, v57, v41
	v_fmac_f32_e32 v35, v61, v41
	v_fmac_f32_e32 v34, v65, v41
	v_fmac_f32_e32 v33, v69, v41
	v_fmac_f32_e32 v32, v73, v41
	s_waitcnt lgkmcnt(0)
; template<int THRL,int MODE,int DM,bool DRY=false> __device__ __forceinline__ void attn_unit(int b,int h,int qb,const bf16*Q,const bf16*__restrict__ K,const bf16*__restrict__ V,bf16*O,const bf16*__restrict__ Z,const float*__restrict__ XP,const int*__restrict__ TS,volatile unsigned*lw,unsigned nxt,cha ...
;     ...
;         _Pragma("unroll") for(int c=0;c<8;++c){ const bf16x8 qv=*reinterpret_cast<const bf16x8*>(qp+c*8);
;           _Pragma("unroll") for(int j=0;j<8;++j){ const float qf=__uint_as_float(((unsigned)(unsigned short)qv[j])<<16);
;             _Pragma("unroll") for(int n=0;n<8;++n)g[n]+=qf*kbs[n*64+c*8+j]; } }
;         m=0u;
;         _Pragma("unroll") for(int it=0;it<3;++it){ float best=-INFINITY; int bi=0;
;           _Pragma("unroll") for(int n=0;n<8;++n){ const bool ok=(n<qb)&&!((m>>n)&1u)&&(g[n]>best); best=ok?g[n]:best; bi=ok?n:bi; }
;           m|=1u<<bi; } }
	v_lshlrev_b32_e32 v40, 16, v114
	v_fmac_f32_e32 v39, v116, v40
	v_fmac_f32_e32 v38, v120, v40
	v_fmac_f32_e32 v37, v124, v40
	v_fmac_f32_e32 v36, v128, v40
	v_fmac_f32_e32 v35, v132, v40
	v_fmac_f32_e32 v34, v136, v40
	v_fmac_f32_e32 v33, v140, v40
	v_fmac_f32_e32 v32, v76, v40
	v_and_b32_e32 v41, 0xffff0000, v114
	v_fmac_f32_e32 v39, v117, v41
	v_fmac_f32_e32 v38, v121, v41
	v_fmac_f32_e32 v37, v125, v41
	v_fmac_f32_e32 v36, v129, v41
	v_fmac_f32_e32 v35, v133, v41
	v_fmac_f32_e32 v34, v137, v41
	v_fmac_f32_e32 v33, v141, v41
	v_fmac_f32_e32 v32, v77, v41
	v_lshlrev_b32_e32 v40, 16, v115
	v_fmac_f32_e32 v39, v118, v40
	v_fmac_f32_e32 v38, v122, v40
	v_fmac_f32_e32 v37, v126, v40
	v_fmac_f32_e32 v36, v130, v40
	v_fmac_f32_e32 v35, v134, v40
	v_fmac_f32_e32 v34, v138, v40
	v_fmac_f32_e32 v33, v142, v40
	v_fmac_f32_e32 v32, v78, v40
	v_and_b32_e32 v41, 0xffff0000, v115
	v_fmac_f32_e32 v39, v119, v41
	v_fmac_f32_e32 v38, v123, v41
	v_fmac_f32_e32 v37, v127, v41
	v_fmac_f32_e32 v36, v131, v41
	v_fmac_f32_e32 v35, v135, v41
	v_fmac_f32_e32 v34, v139, v41
	v_fmac_f32_e32 v33, v143, v41
	v_fmac_f32_e32 v32, v79, v41
	v_cmp_lg_f32_e32 vcc, s10, v39
	s_nop 1
	v_cndmask_b32_e32 v40, v234, v39, vcc
	v_cmp_gt_f32_e32 vcc, v38, v40
	s_nop 1
	v_cndmask_b32_e32 v40, v40, v38, vcc
	v_cndmask_b32_e64 v41, 0, 1, vcc
	v_cmp_gt_f32_e32 vcc, v37, v40
	s_nop 1
	v_cndmask_b32_e32 v40, v40, v37, vcc
	v_cndmask_b32_e64 v41, v41, 2, vcc
	v_cmp_gt_f32_e32 vcc, v36, v40
	s_nop 1
	v_cndmask_b32_e32 v40, v40, v36, vcc
	v_cndmask_b32_e64 v41, v41, 3, vcc
	v_cmp_gt_f32_e32 vcc, v35, v40
	s_and_b64 vcc, s[74:75], vcc
	s_cmp_gt_u32 s95, 5
	v_cndmask_b32_e32 v40, v40, v35, vcc
	v_cndmask_b32_e64 v41, v41, 4, vcc
	s_cselect_b64 s[76:77], -1, 0
	v_cmp_gt_f32_e32 vcc, v34, v40
	s_and_b64 vcc, s[76:77], vcc
	s_cmp_lt_u32 s92, -7
	v_cndmask_b32_e32 v40, v40, v34, vcc
	v_cndmask_b32_e64 v41, v41, 5, vcc
	s_cselect_b64 s[78:79], -1, 0
	v_cmp_gt_f32_e32 vcc, v33, v40
	s_and_b64 vcc, s[78:79], vcc
	s_cmp_gt_u32 s95, 7
	v_cndmask_b32_e32 v40, v40, v33, vcc
	v_cndmask_b32_e64 v41, v41, 6, vcc
	s_cselect_b64 s[80:81], -1, 0
	v_cmp_gt_f32_e32 vcc, v32, v40
	s_and_b64 s[8:9], s[80:81], vcc
	v_cndmask_b32_e64 v40, v41, 7, s[8:9]
	v_cmp_eq_u32_e64 s[8:9], 0, v40
	v_cmp_nlg_f32_e32 vcc, s10, v39
	v_lshlrev_b32_e64 v41, v40, 1
	s_or_b64 s[8:9], s[8:9], vcc
	v_cndmask_b32_e64 v40, v39, v234, s[8:9]
	v_and_b32_e32 v42, 2, v41
	v_cmp_eq_u32_e64 s[8:9], 0, v42
	v_cmp_gt_f32_e64 s[10:11], v38, v40
	s_and_b64 s[8:9], s[8:9], s[10:11]
	v_cndmask_b32_e64 v40, v40, v38, s[8:9]
	v_and_b32_e32 v43, 4, v41
	v_cndmask_b32_e64 v42, 0, 1, s[8:9]
	v_cmp_eq_u32_e64 s[8:9], 0, v43
	v_cmp_gt_f32_e64 s[10:11], v37, v40
	s_and_b64 s[18:19], s[8:9], s[10:11]
	v_cndmask_b32_e64 v40, v40, v37, s[18:19]
	v_and_b32_e32 v43, 8, v41
	v_cmp_eq_u32_e64 s[8:9], 0, v43
	v_cmp_gt_f32_e64 s[10:11], v36, v40
	s_and_b64 s[16:17], s[8:9], s[10:11]
	v_and_b32_e32 v43, 16, v41
	v_cndmask_b32_e64 v40, v40, v36, s[16:17]
	v_cmp_eq_u32_e64 s[8:9], 0, v43
	s_and_b64 s[10:11], s[74:75], s[8:9]
	v_cmp_gt_f32_e64 s[8:9], v35, v40
	s_and_b64 s[14:15], s[10:11], s[8:9]
	v_and_b32_e32 v43, 32, v41
	v_cndmask_b32_e64 v40, v40, v35, s[14:15]
	v_cmp_eq_u32_e64 s[8:9], 0, v43
	s_and_b64 s[10:11], s[76:77], s[8:9]
	v_cmp_gt_f32_e64 s[8:9], v34, v40
	s_and_b64 s[12:13], s[10:11], s[8:9]
	v_and_b32_e32 v43, 64, v41
	v_cndmask_b32_e64 v40, v40, v34, s[12:13]
	v_cmp_eq_u32_e64 s[8:9], 0, v43
	s_and_b64 s[10:11], s[78:79], s[8:9]
	v_cmp_gt_f32_e64 s[8:9], v33, v40
	s_and_b64 s[10:11], s[10:11], s[8:9]
	v_and_b32_e32 v43, 0x80, v41
	v_cndmask_b32_e64 v40, v40, v33, s[10:11]
	v_cmp_eq_u32_e64 s[8:9], 0, v43
	s_and_b64 s[42:43], s[80:81], s[8:9]
	v_cmp_gt_f32_e64 s[8:9], v32, v40
	v_lshlrev_b32_e64 v40, v42, 1
	v_cndmask_b32_e64 v40, v40, 4, s[18:19]
	v_cndmask_b32_e64 v40, v40, 8, s[16:17]
	v_cndmask_b32_e64 v40, v40, 16, s[14:15]
	v_cndmask_b32_e64 v40, v40, 32, s[12:13]
	s_and_b64 s[8:9], s[42:43], s[8:9]
	v_cndmask_b32_e64 v40, v40, 64, s[10:11]
	v_cndmask_b32_e64 v40, v40, v235, s[8:9]
	v_or_b32_e32 v42, v40, v41
	v_and_b32_e32 v43, 1, v42
	v_cmp_eq_u32_e64 s[8:9], 1, v43
	s_or_b64 vcc, s[8:9], vcc
	v_cndmask_b32_e32 v39, v39, v234, vcc
	v_bitop3_b32 v43, v40, 2, v41 bitop3:0xc8
	v_cmp_eq_u32_e32 vcc, 0, v43
	v_cmp_gt_f32_e64 s[8:9], v38, v39
	s_and_b64 vcc, vcc, s[8:9]
	v_cndmask_b32_e32 v38, v39, v38, vcc
	v_bitop3_b32 v39, v40, 4, v41 bitop3:0xc8
	v_cndmask_b32_e64 v43, 0, 1, vcc
	v_cmp_eq_u32_e32 vcc, 0, v39
	v_cmp_gt_f32_e64 s[8:9], v37, v38
	s_and_b64 s[8:9], vcc, s[8:9]
	s_nop 0
	v_cndmask_b32_e64 v37, v38, v37, s[8:9]
	v_bitop3_b32 v38, v40, 8, v41 bitop3:0xc8
	v_cmp_eq_u32_e32 vcc, 0, v38
	v_cmp_gt_f32_e64 s[10:11], v36, v37
	s_and_b64 vcc, vcc, s[10:11]
	v_cndmask_b32_e32 v36, v37, v36, vcc
	v_bitop3_b32 v37, v40, 16, v41 bitop3:0xc8
	v_cmp_eq_u32_e64 s[10:11], 0, v37
	s_and_b64 s[12:13], s[74:75], s[10:11]
	v_cmp_gt_f32_e64 s[10:11], v35, v36
	s_and_b64 s[10:11], s[12:13], s[10:11]
	s_nop 0
	v_cndmask_b32_e64 v35, v36, v35, s[10:11]
	v_bitop3_b32 v36, v40, 32, v41 bitop3:0xc8
	v_cmp_eq_u32_e64 s[12:13], 0, v36
	s_and_b64 s[14:15], s[76:77], s[12:13]
	v_cmp_gt_f32_e64 s[12:13], v34, v35
	s_and_b64 s[12:13], s[14:15], s[12:13]
	s_nop 0
	v_cndmask_b32_e64 v34, v35, v34, s[12:13]
	v_bitop3_b32 v35, v40, 64, v41 bitop3:0xc8
	v_cmp_eq_u32_e64 s[14:15], 0, v35
	s_and_b64 s[16:17], s[78:79], s[14:15]
	v_cmp_gt_f32_e64 s[14:15], v33, v34
	s_and_b64 s[14:15], s[16:17], s[14:15]
	s_movk_i32 s16, 0x80
	v_cndmask_b32_e64 v33, v34, v33, s[14:15]
	v_bitop3_b32 v34, v40, s16, v41 bitop3:0xc8
	v_cmp_eq_u32_e64 s[16:17], 0, v34
	s_and_b64 s[18:19], s[80:81], s[16:17]
	v_cmp_gt_f32_e64 s[16:17], v32, v33
	v_lshlrev_b32_e64 v32, v43, 1
	v_cndmask_b32_e64 v32, v32, 4, s[8:9]
	v_cndmask_b32_e64 v32, v32, 8, vcc
	v_cndmask_b32_e64 v32, v32, 16, s[10:11]
	v_cndmask_b32_e64 v32, v32, 32, s[12:13]
	s_and_b64 s[16:17], s[18:19], s[16:17]
	v_cndmask_b32_e64 v32, v32, 64, s[14:15]
	v_cndmask_b32_e64 v32, v32, v235, s[16:17]
	v_readlane_b32 s78, v253, 1
	v_or_b32_e32 v32, v32, v42
	v_readlane_b32 s79, v253, 2
